# re-measure: attention softmax+PV reschedule + s_sleep 8 per tile
# baseline (speedup 1.0000x reference)
; #define MFMA32(a, b, c) __builtin_amdgcn_mfma_f32_32x32x16_bf16((a), (b), (c), 0, 0, 0)
; DI void attn_phase(ldsp lds, const bf16_t* Q, const bf16_t* KN, const bf16_t* KR, const bf16_t* VT, bf16_t* O, int vcu, int G) {
;     ...
;                     float rs = 0.f;
; #pragma unroll
;                     for (int r = 0; r < 16; ++r) { s0[r] = __builtin_amdgcn_exp2f(s0[r] - mrun); s1[r] = __builtin_amdgcn_exp2f(s1[r] - mrun); rs += s0[r] + s1[r]; }
;                     lrun += rs;
;                     bf16x8 pa[2][2];
;                     pa[0][0] = pack8(s0, 0); pa[0][1] = pack8(s0, 1); pa[1][0] = pack8(s1, 0); pa[1][1] = pack8(s1, 1);
; #pragma unroll
;                     for (int kb2 = 0; kb2 < 2; ++kb2)
; #pragma unroll
;                         for (int s2 = 0; s2 < 2; ++s2)
; #pragma unroll
;                             for (int d = 0; d < 4; ++d) {
;                                 const bf16x8 va = lds_8x2(Lb + AT_VOFF + (d * 32 + l31) * AT_VP + (kb2 * 32 + 16 * s2 + 4 * hh) * 2, 16);
;                                 o[d] = MFMA32(va, pa[kb2][s2], o[d]); }
.LBB0_1458:
	s_sleep 8
	v_sub_f32_e32 v82, v82, v229
	v_sub_f32_e32 v83, v83, v229
	v_sub_f32_e32 v84, v84, v229
	v_sub_f32_e32 v85, v85, v229
	v_sub_f32_e32 v86, v86, v229
	v_sub_f32_e32 v87, v87, v229
	v_sub_f32_e32 v88, v88, v229
	v_sub_f32_e32 v89, v89, v229
	v_exp_f32_e32 v82, v82
	v_exp_f32_e32 v83, v83
	v_exp_f32_e32 v84, v84
	v_exp_f32_e32 v85, v85
	v_exp_f32_e32 v86, v86
	v_exp_f32_e32 v87, v87
	v_exp_f32_e32 v88, v88
	v_exp_f32_e32 v89, v89
	v_add_f32_e32 v1, v82, v84
	v_add_f32_e32 v230, v83, v85
	v_add_f32_e32 v1, v1, v86
	v_add_f32_e32 v230, v230, v87
	v_add_f32_e32 v1, v1, v88
	v_add_f32_e32 v230, v230, v89
	v_cvt_pk_bf16_f32 v82, v82, v83
	v_cvt_pk_bf16_f32 v83, v84, v85
	v_cvt_pk_bf16_f32 v84, v86, v87
	v_cvt_pk_bf16_f32 v85, v88, v89
	s_nop 1
	s_waitcnt lgkmcnt(8)
	v_mfma_f32_32x32x16_bf16 v[50:65], v[232:235], v[82:85], v[50:65]
	ds_read_b64 v[232:233], v253 offset:29984
	ds_read_b64 v[234:235], v253 offset:30000
	v_sub_f32_e32 v90, v90, v229
	v_sub_f32_e32 v91, v91, v229
	v_sub_f32_e32 v92, v92, v229
	v_sub_f32_e32 v93, v93, v229
	v_sub_f32_e32 v94, v94, v229
	v_sub_f32_e32 v95, v95, v229
	v_sub_f32_e32 v96, v96, v229
	s_waitcnt lgkmcnt(8)
	v_mfma_f32_32x32x16_bf16 v[34:49], v[236:239], v[82:85], v[34:49]
	ds_read_b64 v[236:237], v253 offset:34336
	ds_read_b64 v[238:239], v253 offset:34352
	v_sub_f32_e32 v97, v97, v229
	v_exp_f32_e32 v90, v90
	v_exp_f32_e32 v91, v91
	v_exp_f32_e32 v92, v92
	v_exp_f32_e32 v93, v93
	v_exp_f32_e32 v94, v94
	v_exp_f32_e32 v95, v95
	s_waitcnt lgkmcnt(8)
	v_mfma_f32_32x32x16_bf16 v[18:33], v[240:243], v[82:85], v[18:33]
	ds_read_b64 v[240:241], v253 offset:38688
	ds_read_b64 v[242:243], v253 offset:38704
	v_exp_f32_e32 v96, v96
	v_exp_f32_e32 v97, v97
	v_add_f32_e32 v1, v1, v90
	v_add_f32_e32 v230, v230, v91
	v_add_f32_e32 v1, v1, v92
	v_add_f32_e32 v230, v230, v93
	v_add_f32_e32 v1, v1, v94
	s_waitcnt lgkmcnt(8)
	v_mfma_f32_32x32x16_bf16 v[2:17], v[244:247], v[82:85], v[2:17]
	ds_read_b64 v[244:245], v253 offset:25664
	ds_read_b64 v[246:247], v253 offset:25680
	v_add_f32_e32 v230, v230, v95
	v_add_f32_e32 v1, v1, v96
	v_add_f32_e32 v230, v230, v97
	v_cvt_pk_bf16_f32 v90, v90, v91
	v_cvt_pk_bf16_f32 v91, v92, v93
	v_cvt_pk_bf16_f32 v92, v94, v95
	v_cvt_pk_bf16_f32 v93, v96, v97
	s_nop 1
	s_waitcnt lgkmcnt(8)
	v_mfma_f32_32x32x16_bf16 v[50:65], v[248:251], v[90:93], v[50:65]
	ds_read_b64 v[248:249], v253 offset:30016
	ds_read_b64 v[250:251], v253 offset:30032
	v_sub_f32_e32 v66, v66, v229
	v_sub_f32_e32 v67, v67, v229
	v_sub_f32_e32 v68, v68, v229
	v_sub_f32_e32 v69, v69, v229
	v_sub_f32_e32 v70, v70, v229
	v_sub_f32_e32 v71, v71, v229
	v_sub_f32_e32 v72, v72, v229
	s_waitcnt lgkmcnt(8)
	v_mfma_f32_32x32x16_bf16 v[34:49], v[232:235], v[90:93], v[34:49]
	ds_read_b64 v[232:233], v253 offset:34368
	ds_read_b64 v[234:235], v253 offset:34384
	v_sub_f32_e32 v73, v73, v229
	v_exp_f32_e32 v66, v66
	v_exp_f32_e32 v67, v67
	v_exp_f32_e32 v68, v68
	v_exp_f32_e32 v69, v69
	v_exp_f32_e32 v70, v70
	v_exp_f32_e32 v71, v71
	s_waitcnt lgkmcnt(8)
	v_mfma_f32_32x32x16_bf16 v[18:33], v[236:239], v[90:93], v[18:33]
	ds_read_b64 v[236:237], v253 offset:38720
	ds_read_b64 v[238:239], v253 offset:38736
	v_exp_f32_e32 v72, v72
	v_exp_f32_e32 v73, v73
	v_add_f32_e32 v1, v1, v66
	v_add_f32_e32 v230, v230, v67
	v_add_f32_e32 v1, v1, v68
	v_add_f32_e32 v230, v230, v69
	v_add_f32_e32 v1, v1, v70
	s_waitcnt lgkmcnt(8)
	v_mfma_f32_32x32x16_bf16 v[2:17], v[240:243], v[90:93], v[2:17]
	ds_read_b64 v[240:241], v253 offset:25696
	ds_read_b64 v[242:243], v253 offset:25712
	v_add_f32_e32 v230, v230, v71
	v_add_f32_e32 v1, v1, v72
	v_add_f32_e32 v230, v230, v73
	v_cvt_pk_bf16_f32 v66, v66, v67
	v_cvt_pk_bf16_f32 v67, v68, v69
	v_cvt_pk_bf16_f32 v68, v70, v71
	v_cvt_pk_bf16_f32 v69, v72, v73
	s_nop 1
	s_waitcnt lgkmcnt(8)
	v_mfma_f32_32x32x16_bf16 v[50:65], v[244:247], v[66:69], v[50:65]
	ds_read_b64 v[244:245], v253 offset:30048
	ds_read_b64 v[246:247], v253 offset:30064
	v_sub_f32_e32 v74, v74, v229
	v_sub_f32_e32 v75, v75, v229
	v_sub_f32_e32 v76, v76, v229
	v_sub_f32_e32 v77, v77, v229
	v_sub_f32_e32 v78, v78, v229
	v_sub_f32_e32 v79, v79, v229
	v_sub_f32_e32 v80, v80, v229
	s_waitcnt lgkmcnt(8)
	v_mfma_f32_32x32x16_bf16 v[34:49], v[248:251], v[66:69], v[34:49]
	ds_read_b64 v[248:249], v253 offset:34400
	ds_read_b64 v[250:251], v253 offset:34416
	v_sub_f32_e32 v81, v81, v229
	v_exp_f32_e32 v74, v74
	v_exp_f32_e32 v75, v75
	v_exp_f32_e32 v76, v76
	v_exp_f32_e32 v77, v77
	v_exp_f32_e32 v78, v78
	v_exp_f32_e32 v79, v79
	s_waitcnt lgkmcnt(8)
	v_mfma_f32_32x32x16_bf16 v[18:33], v[232:235], v[66:69], v[18:33]
	ds_read_b64 v[232:233], v253 offset:38752
	ds_read_b64 v[234:235], v253 offset:38768
	v_exp_f32_e32 v80, v80
	v_exp_f32_e32 v81, v81
	v_add_f32_e32 v1, v1, v74
	v_add_f32_e32 v230, v230, v75
	v_add_f32_e32 v1, v1, v76
	v_add_f32_e32 v230, v230, v77
	v_add_f32_e32 v1, v1, v78
	s_waitcnt lgkmcnt(8)
	v_mfma_f32_32x32x16_bf16 v[2:17], v[236:239], v[66:69], v[2:17]
	v_add_f32_e32 v230, v230, v79
	v_add_f32_e32 v1, v1, v80
	v_add_f32_e32 v230, v230, v81
	v_cvt_pk_bf16_f32 v74, v74, v75
	v_cvt_pk_bf16_f32 v75, v76, v77
	v_cvt_pk_bf16_f32 v76, v78, v79
	v_cvt_pk_bf16_f32 v77, v80, v81
	s_nop 1
	s_waitcnt lgkmcnt(6)
	v_mfma_f32_32x32x16_bf16 v[50:65], v[240:243], v[74:77], v[50:65]
	s_waitcnt lgkmcnt(4)
	v_mfma_f32_32x32x16_bf16 v[34:49], v[244:247], v[74:77], v[34:49]
	s_waitcnt lgkmcnt(2)
	v_mfma_f32_32x32x16_bf16 v[18:33], v[248:251], v[74:77], v[18:33]
	s_waitcnt lgkmcnt(0)
	v_mfma_f32_32x32x16_bf16 v[2:17], v[232:235], v[74:77], v[2:17]
	v_add_f32_e32 v1, v1, v230
	v_add_f32_e32 v227, v227, v1
	s_andn2_b64 vcc, exec, s[16:17]
	s_cbranch_vccnz .LBB0_1449
